# v52 + attention prologue: CL loads issued without waiting for K/V/Q DMA, queue atomic non-blocking after first barrier
# speedup vs baseline: 1.0080x; 1.0080x over previous
.LBB0_549:
	s_or_b64 exec, exec, s[0:1]
	v_add_u32_e32 v4, 0x800, v4
	v_cmp_le_i32_e32 vcc, s20, v4
	v_add_u32_e32 v0, 0x2000, v0
	s_or_b64 s[64:65], vcc, s[64:65]
	v_lshl_add_u64 v[2:3], v[2:3], 0, s[26:27]
	s_andn2_b64 exec, exec, s[64:65]
	s_cbranch_execz .LBB0_556
	s_waitcnt vmcnt(0)
.LBB0_550:
	v_add_u32_e32 v5, 0x400, v4
	v_cmp_gt_i32_e64 s[0:1], s20, v5
	global_load_dword v10, v[2:3], off
	s_nop 0
	v_cndmask_b32_e64 v6, 0, v5, s[0:1]
	v_add_u32_e32 v5, 0x600, v4
	v_cmp_gt_i32_e32 vcc, s20, v5
	v_ashrrev_i32_e32 v7, 31, v6
	v_lshl_add_u64 v[6:7], v[6:7], 2, s[62:63]
	v_cndmask_b32_e32 v8, 0, v5, vcc
	v_ashrrev_i32_e32 v9, 31, v8
	v_lshl_add_u64 v[8:9], v[8:9], 2, s[62:63]
	global_load_dword v7, v[6:7], off
	s_nop 0
	global_load_dword v5, v[8:9], off
	v_add_u32_e32 v6, s16, v4
	v_ashrrev_i32_e32 v8, 6, v6
	v_lshl_add_u32 v8, v8, 2, s56
	ds_read_b32 v9, v8
	v_add_u32_e32 v8, 0x200, v4
	v_cmp_gt_i32_e64 s[8:9], s20, v8
	s_waitcnt vmcnt(2) lgkmcnt(0)
	v_add_f32_e32 v9, v10, v9
	v_mul_f32_e32 v9, 0x3fb8aa3b, v9
	v_add_u32_e32 v10, 0xffffe800, v0
	ds_write_b32 v10, v9
	s_and_saveexec_b64 s[66:67], s[8:9]
	s_cbranch_execnz .LBB0_553
	s_or_b64 exec, exec, s[66:67]
	s_and_saveexec_b64 s[8:9], s[0:1]
	s_cbranch_execnz .LBB0_554

.LBB0_560:
	s_or_b64 exec, exec, s[0:1]
	v_lshlrev_b32_e32 v0, 10, v208
	v_lshlrev_b32_e32 v2, 4, v207
	v_add3_u32 v216, 0, v0, v2
	s_waitcnt vmcnt(3) lgkmcnt(0)
	s_barrier
	s_waitcnt vmcnt(0)
	s_and_saveexec_b64 s[0:1], s[56:57]
	s_cbranch_execz .Lmy_w2_skip
	v_mov_b32_e32 v0, 1
	global_atomic_add v210, v1, v0, s[18:19] sc0
.Lmy_w2_skip:
	s_or_b64 exec, exec, s[0:1]
	ds_read_b128 v[2:5], v216
	ds_read_b128 v[20:23], v216 offset:512
	v_lshlrev_b32_e32 v217, 4, v208
	v_add_u32_e32 v0, 0, v217
	v_add_u32_e32 v0, 0x14800, v0
	s_lshr_b32 s11, s11, 6
	s_sub_i32 s86, s11, s10
	s_waitcnt lgkmcnt(0)
	v_mfma_f32_32x32x16_bf16 v[32:47], v[20:23], v[124:127], 0
	ds_read_b128 v[20:23], v216 offset:2048
	v_or_b32_e32 v215, s82, v207
	v_mfma_f32_32x32x16_bf16 v[4:19], v[2:5], v[124:127], 0
	s_waitcnt lgkmcnt(0)
	v_mfma_f32_32x32x16_bf16 v[4:19], v[20:23], v[120:123], v[4:19]
	ds_read_b128 v[20:23], v216 offset:2560
	s_waitcnt lgkmcnt(0)
	v_mfma_f32_32x32x16_bf16 v[32:47], v[20:23], v[120:123], v[32:47]
	ds_read_b128 v[20:23], v216 offset:4096
	s_waitcnt lgkmcnt(0)
	v_mfma_f32_32x32x16_bf16 v[4:19], v[20:23], v[116:119], v[4:19]
	ds_read_b128 v[20:23], v216 offset:4608
	s_waitcnt lgkmcnt(0)
	v_mfma_f32_32x32x16_bf16 v[32:47], v[20:23], v[116:119], v[32:47]
	ds_read_b128 v[20:23], v216 offset:6144
	s_waitcnt lgkmcnt(0)
	v_mfma_f32_32x32x16_bf16 v[4:19], v[20:23], v[112:115], v[4:19]
	ds_read_b128 v[20:23], v216 offset:6656
	s_waitcnt lgkmcnt(0)
	v_mfma_f32_32x32x16_bf16 v[32:47], v[20:23], v[112:115], v[32:47]
	s_nop 15
	s_nop 7
	ds_read_b128 v[20:23], v0
	ds_read_b128 v[24:27], v0 offset:128
	ds_read_b128 v[28:31], v0 offset:32
	ds_read_b128 v[50:53], v0 offset:160
	ds_read_b128 v[54:57], v0 offset:64
	ds_read_b128 v[58:61], v0 offset:192
	ds_read_b128 v[62:65], v0 offset:96
	ds_read_b128 v[66:69], v0 offset:224
	s_waitcnt lgkmcnt(7)
	v_sub_f32_e32 v3, v7, v23
	v_sub_f32_e32 v2, v6, v22
	v_sub_f32_e32 v23, v5, v21
	v_sub_f32_e32 v0, v4, v20
	s_waitcnt lgkmcnt(5)
	v_sub_f32_e32 v7, v11, v31
	v_sub_f32_e32 v6, v10, v30
	v_sub_f32_e32 v5, v9, v29
	v_sub_f32_e32 v4, v8, v28
	s_waitcnt lgkmcnt(3)
	v_sub_f32_e32 v11, v15, v57
	v_sub_f32_e32 v10, v14, v56
	v_sub_f32_e32 v9, v13, v55
	v_sub_f32_e32 v8, v12, v54
	s_waitcnt lgkmcnt(1)
	v_sub_f32_e32 v15, v19, v65
	v_sub_f32_e32 v14, v18, v64
	v_sub_f32_e32 v13, v17, v63
	v_sub_f32_e32 v12, v16, v62
	v_sub_f32_e32 v31, v35, v27
	v_sub_f32_e32 v28, v34, v26
	v_sub_f32_e32 v33, v33, v25
	v_sub_f32_e32 v30, v32, v24
	v_sub_f32_e32 v27, v39, v53
	v_sub_f32_e32 v24, v38, v52
	v_sub_f32_e32 v29, v37, v51
	v_sub_f32_e32 v26, v36, v50
	v_sub_f32_e32 v21, v43, v61
	v_sub_f32_e32 v20, v42, v60
	v_sub_f32_e32 v25, v41, v59
	v_sub_f32_e32 v22, v40, v58
	s_waitcnt lgkmcnt(0)
	v_sub_f32_e32 v17, v47, v69
	v_sub_f32_e32 v16, v46, v68
	v_sub_f32_e32 v19, v45, v67
	v_sub_f32_e32 v18, v44, v66
	s_cmp_gt_i32 s86, 4
	v_lshlrev_b32_e32 v211, 2, v208
	s_cbranch_scc1 .LBB0_562
	s_lshl_b32 s0, s86, 6
	v_subrev_u32_e32 v32, s0, v211
	v_add_u32_e32 v35, 0x120, v32
	v_add_u32_e32 v34, 0x100, v32
	v_cmp_le_i32_e64 s[0:1], v35, v215
	v_cmp_le_i32_e32 vcc, v34, v215
	s_nop 0
	v_cndmask_b32_e64 v30, v204, v30, s[0:1]
	v_cmp_lt_i32_e64 s[0:1], v34, v215
	v_add_u32_e32 v34, 0x121, v32
	v_cndmask_b32_e32 v0, v204, v0, vcc
	v_cmp_le_i32_e32 vcc, v34, v215
	v_add_u32_e32 v34, 0x102, v32
	v_cndmask_b32_e64 v23, v204, v23, s[0:1]
	v_cndmask_b32_e32 v33, v204, v33, vcc
	v_cmp_le_i32_e32 vcc, v34, v215
	v_add_u32_e32 v34, 0x122, v32
	s_nop 0
	v_cndmask_b32_e32 v2, v204, v2, vcc
	v_cmp_le_i32_e32 vcc, v34, v215
	v_add_u32_e32 v34, 0x103, v32
	s_nop 0
	v_cndmask_b32_e32 v28, v204, v28, vcc
	v_cmp_le_i32_e32 vcc, v34, v215
	v_add_u32_e32 v34, 0x123, v32
	s_nop 0
	v_cndmask_b32_e32 v3, v204, v3, vcc
	v_cmp_le_i32_e32 vcc, v34, v215
	v_add_u32_e32 v34, 0x108, v32
	s_nop 0
	v_cndmask_b32_e32 v31, v204, v31, vcc
	v_cmp_le_i32_e32 vcc, v34, v215
	v_add_u32_e32 v34, 0x128, v32
	s_nop 0
	v_cndmask_b32_e32 v4, v204, v4, vcc
	v_cmp_le_i32_e32 vcc, v34, v215
	v_add_u32_e32 v34, 0x109, v32
	s_nop 0
	v_cndmask_b32_e32 v26, v204, v26, vcc
	v_cmp_le_i32_e32 vcc, v34, v215
	v_add_u32_e32 v34, 0x129, v32
	s_nop 0
	v_cndmask_b32_e32 v5, v204, v5, vcc
	v_cmp_le_i32_e32 vcc, v34, v215
	v_add_u32_e32 v34, 0x10a, v32
	s_nop 0
	v_cndmask_b32_e32 v29, v204, v29, vcc
	v_cmp_le_i32_e32 vcc, v34, v215
	v_add_u32_e32 v34, 0x12a, v32
	s_nop 0
	v_cndmask_b32_e32 v6, v204, v6, vcc
	v_cmp_le_i32_e32 vcc, v34, v215
	v_add_u32_e32 v34, 0x10b, v32
	s_nop 0
	v_cndmask_b32_e32 v24, v204, v24, vcc
	v_cmp_le_i32_e32 vcc, v34, v215
	v_add_u32_e32 v34, 0x12b, v32
	s_nop 0
	v_cndmask_b32_e32 v7, v204, v7, vcc
	v_cmp_le_i32_e32 vcc, v34, v215
	v_add_u32_e32 v34, 0x110, v32
	s_nop 0
	v_cndmask_b32_e32 v27, v204, v27, vcc
	v_cmp_le_i32_e32 vcc, v34, v215
	v_add_u32_e32 v34, 0x130, v32
	s_nop 0
	v_cndmask_b32_e32 v8, v204, v8, vcc
	v_cmp_le_i32_e32 vcc, v34, v215
	v_add_u32_e32 v34, 0x111, v32
	s_nop 0
	v_cndmask_b32_e32 v22, v204, v22, vcc
	v_cmp_le_i32_e32 vcc, v34, v215
	v_add_u32_e32 v34, 0x131, v32
	s_nop 0
	v_cndmask_b32_e32 v9, v204, v9, vcc
	v_cmp_le_i32_e32 vcc, v34, v215
	v_add_u32_e32 v34, 0x112, v32
	s_nop 0
	v_cndmask_b32_e32 v25, v204, v25, vcc
	v_cmp_le_i32_e32 vcc, v34, v215
	v_add_u32_e32 v34, 0x132, v32
	s_nop 0
	v_cndmask_b32_e32 v10, v204, v10, vcc
	v_cmp_le_i32_e32 vcc, v34, v215
	v_add_u32_e32 v34, 0x113, v32
	s_nop 0
	v_cndmask_b32_e32 v20, v204, v20, vcc
	v_cmp_le_i32_e32 vcc, v34, v215
	v_add_u32_e32 v34, 0x133, v32
	s_nop 0
	v_cndmask_b32_e32 v11, v204, v11, vcc
	v_cmp_le_i32_e32 vcc, v34, v215
	v_add_u32_e32 v34, 0x118, v32
	s_nop 0
	v_cndmask_b32_e32 v21, v204, v21, vcc
	v_cmp_le_i32_e32 vcc, v34, v215
	v_add_u32_e32 v34, 0x138, v32
	s_nop 0
	v_cndmask_b32_e32 v12, v204, v12, vcc
	v_cmp_le_i32_e32 vcc, v34, v215
	v_add_u32_e32 v34, 0x119, v32
	s_nop 0
	v_cndmask_b32_e32 v18, v204, v18, vcc
	v_cmp_le_i32_e32 vcc, v34, v215
	v_add_u32_e32 v34, 0x139, v32
	s_nop 0
	v_cndmask_b32_e32 v13, v204, v13, vcc
	v_cmp_le_i32_e32 vcc, v34, v215
	v_add_u32_e32 v34, 0x11a, v32
	s_nop 0
	v_cndmask_b32_e32 v19, v204, v19, vcc
	v_cmp_le_i32_e32 vcc, v34, v215
	v_add_u32_e32 v34, 0x13a, v32
	s_nop 0
	v_cndmask_b32_e32 v14, v204, v14, vcc
	v_cmp_le_i32_e32 vcc, v34, v215
	v_add_u32_e32 v34, 0x11b, v32
	v_add_u32_e32 v32, 0x13b, v32
	v_cndmask_b32_e32 v16, v204, v16, vcc
	v_cmp_le_i32_e32 vcc, v34, v215
	s_nop 1
	v_cndmask_b32_e32 v15, v204, v15, vcc
	v_cmp_le_i32_e32 vcc, v32, v215
	s_nop 1
	v_cndmask_b32_e32 v17, v204, v17, vcc
